# phase 8: the 128 workgroups without a 13th GEMM tile do phase 9's W1Z/W1OUT transposes during the last half round (gated by a 12th-tile-done counter)
# baseline (speedup 1.0000x reference)
; __device__ void lru_carry(const Params& p) {
;     const float* LA = (const float*)(p.ws + OFF_LRUA); const float* LH = (const float*)(p.ws + OFF_LRUH); float* LC = (float*)(p.ws + OFF_LRUC);
;     for (int idx = blockIdx.x * 512 + threadIdx.x; idx < 4 * 2048; idx += gridDim.x * 512) { const int b = idx >> 11, cg_ = idx & 2047; float c = 0.f;
; #pragma unroll 8
;         for (int k = 0; k < 64; ++k) { const size_t o = (size_t)(b * 64 + k) * 2048 + cg_; LC[o] = c; c = LA[o] * c + LH[o]; } }
; }
.LBB0_310:
	v_and_b32_e32 v70, 0x3ff, v0
	v_lshl_or_b32 v70, s70, 9, v70
	v_cmp_gt_u32_e32 vcc, 0x2001, v70
	s_and_saveexec_b64 s[2:3], vcc
	s_cbranch_execz LRUX_zskip
	s_add_u32 s4, s64, 0x1f500000
	s_addc_u32 s5, s65, 0
	v_lshlrev_b32_e32 v70, 2, v70
	v_mov_b32_e32 v71, 0
	global_store_dword v70, v71, s[4:5] sc0 sc1

;     __host__ __device__ bool next(int i, Unit& u) const {
;         const long L = (long)i * G + c; if (L >= nwg) return false;
;         int wgid = (int)L; { const int q = nwg / NXCD, r = nwg % NXCD, xcd = wgid % NXCD, off = wgid / NXCD; wgid = (xcd < r ? xcd * (q + 1) : r * (q + 1) + (xcd - r) * q) + off; }
;         const int nig = WGM * nN, gid = wgid / nig, fm = gid * WGM, gsz = (nM - fm) < WGM ? (nM - fm) : WGM;
;         u.pm = fm + ((wgid % nig) % gsz); u.pn = (wgid % nig) / gsz; return true;
;     }
; template <class Epi>
; __device__ __forceinline__ void gemm_phase(PG8_LAS unsigned char* lds, const Gemm g, const StaticOrder& S, const Epi& E) {
;     ...
;         const bool has_next = S.next(ui + 1, nxt);
.LBB0_719:
	s_cmp_eq_u32 s35, 12
	s_cbranch_scc0 P8DONE_skip
	v_and_b32_e32 v2, 0x3fffffff, v0
	v_cmp_eq_u32_e32 vcc, 0, v2
	s_and_saveexec_b64 s[54:55], vcc
	s_cbranch_execz P8DONE_ex
	s_add_u32 s52, s64, 0x1f508000
	s_addc_u32 s53, s65, 0
	v_mov_b32_e32 v2, 1
	v_mov_b32_e32 v3, 0
	global_atomic_add v3, v2, s[52:53]
P8DONE_ex:
	s_mov_b64 exec, s[54:55]
P8DONE_skip:
	s_add_i32 s35, s35, 1
	s_mul_i32 s0, s35, s40
	s_mul_hi_u32 s1, s35, s62
	s_add_i32 s1, s1, s0
	s_mul_i32 s0, s35, s62
	s_add_u32 s16, s0, s70
	s_addc_u32 s17, s1, s41
	v_cmp_gt_i64_e64 s[0:1], s[16:17], v[148:149]
	s_and_b64 vcc, exec, s[0:1]
	s_cbranch_vccnz .LBB0_721
	s_ashr_i32 s3, s16, 31
	s_lshr_b32 s3, s3, 29
	s_add_i32 s3, s16, s3
	s_ashr_i32 s5, s3, 3
	s_and_b32 s3, s3, -8
	s_sub_i32 s3, s16, s3
	s_cmp_lt_i32 s3, 0
	s_cselect_b32 s12, s42, 0x190
	s_mul_i32 s3, s3, s12
	s_add_i32 s3, s3, s5
	s_mul_hi_i32 s5, s3, 0x51eb851f
	s_lshr_b32 s12, s5, 31
	s_ashr_i32 s5, s5, 7
	s_add_i32 s5, s5, s12
	s_lshl_b32 s13, s5, 3
	s_sub_i32 s12, 64, s13
	s_min_i32 s14, s12, 8
	s_abs_i32 s12, s14
	v_cvt_f32_u32_e32 v2, s12
	s_sub_i32 s18, 0, s12
	s_mulk_i32 s5, 0x190
	s_sub_i32 s3, s3, s5
	v_rcp_iflag_f32_e32 v2, v2
	s_abs_i32 s5, s3
	s_xor_b32 s15, s3, s14
	s_ashr_i32 s15, s15, 31
	v_mul_f32_e32 v2, 0x4f7ffffe, v2
	v_cvt_u32_f32_e32 v2, v2
	s_nop 0
	v_readfirstlane_b32 s19, v2
	s_mul_i32 s18, s18, s19
	s_mul_hi_u32 s18, s19, s18
	s_add_i32 s19, s19, s18
	s_mul_hi_u32 s18, s5, s19
	s_mul_i32 s19, s18, s12
	s_sub_i32 s5, s5, s19
	s_add_i32 s24, s18, 1
	s_sub_i32 s19, s5, s12
	s_cmp_ge_u32 s5, s12
	s_cselect_b32 s18, s24, s18
	s_cselect_b32 s5, s19, s5
	s_add_i32 s19, s18, 1
	s_cmp_ge_u32 s5, s12
	s_cselect_b32 s5, s19, s18
	s_xor_b32 s5, s5, s15
	s_sub_i32 s12, s5, s15
	s_mul_i32 s5, s12, s14
	s_sub_i32 s3, s3, s5
	s_add_i32 s14, s13, s3

; __device__ __forceinline__ u32x4 pack8(const float* f) { u32x4 w; w.x = pk2(f[0], f[1]); w.y = pk2(f[2], f[3]); w.z = pk2(f[4], f[5]); w.w = pk2(f[6], f[7]); return w; }
; __device__ void tconv(unsigned char* smem, const float* src, int ldsrc, int col0, int N, int K, u16* dst, int ldd) {
;     float* T = (float*)smem;
;     const int tid = threadIdx.x, tilesN = N >> 6, ntile = tilesN * (K >> 6);
;     const int lr = tid >> 4, lc = (tid & 15) * 4;
;     const int sn = tid >> 3, sk = (tid & 7) * 8;
;     int tile = blockIdx.x;
;     f32x4 v0 = {0.f, 0.f, 0.f, 0.f}, v1 = {0.f, 0.f, 0.f, 0.f};
;     if (tile < ntile) { const int tn = tile % tilesN, tk = tile / tilesN; const float* s = src + (size_t)(tk * 64 + lr) * ldsrc + col0 + tn * 64 + lc;
;         v0 = __builtin_nontemporal_load((const f32x4*)s); v1 = __builtin_nontemporal_load((const f32x4*)(s + (size_t)32 * ldsrc)); }
;     for (; tile < ntile; tile += gridDim.x) {
;         const int tn = tile % tilesN, tk = tile / tilesN;
; #pragma unroll
;         for (int j = 0; j < 4; ++j) { T[lr * 65 + lc + j] = v0[j]; T[(lr + 32) * 65 + lc + j] = v1[j]; }
;         asm volatile("s_waitcnt lgkmcnt(0)" ::: "memory"); __builtin_amdgcn_s_barrier(); asm volatile("" ::: "memory");
;         const int nx = tile + gridDim.x;
;         if (nx < ntile) { const int tn2 = nx % tilesN, tk2 = nx / tilesN; const float* s = src + (size_t)(tk2 * 64 + lr) * ldsrc + col0 + tn2 * 64 + lc;
;             v0 = __builtin_nontemporal_load((const f32x4*)s); v1 = __builtin_nontemporal_load((const f32x4*)(s + (size_t)32 * ldsrc)); }
;         float f[8];
; #pragma unroll
;         for (int j = 0; j < 8; ++j) f[j] = T[(sk + j) * 65 + sn];
;         *(u32x4*)(dst + (size_t)(tn * 64 + sn) * ldd + tk * 64 + sk) = pack8(f);
;         asm volatile("s_waitcnt lgkmcnt(0)" ::: "memory"); __builtin_amdgcn_s_barrier(); asm volatile("" ::: "memory");
;     }
;     __syncthreads();
.LBB0_813:
	s_barrier
	s_cmpk_lt_u32 s70, 0x80
	s_cbranch_scc1 P8IDLE_skip
	v_and_b32_e32 v2, 0x3fffffff, v0
	v_cmp_eq_u32_e32 vcc, 0, v2
	s_and_saveexec_b64 s[54:55], vcc
	s_cbranch_execz P8IDLE_polled
	s_add_u32 s52, s64, 0x1f508000
	s_addc_u32 s53, s65, 0
	v_mov_b32_e32 v2, 1
	v_mov_b32_e32 v3, 0
	global_atomic_add v3, v2, s[52:53]
	s_movk_i32 s56, 0x2000
P8IDLE_poll:
	global_load_dword v2, v3, s[52:53] sc1
	s_waitcnt vmcnt(0)
	v_cmp_gt_u32_e32 vcc, s62, v2
	s_cbranch_vccz P8IDLE_polled
	s_add_i32 s56, s56, -1
	s_cmp_eq_u32 s56, 0
	s_cbranch_scc1 P8IDLE_polled
	s_sleep 4
	s_branch P8IDLE_poll
P8IDLE_polled:
	s_mov_b64 exec, s[54:55]
	s_barrier
	s_waitcnt vmcnt(0) lgkmcnt(0)
	s_barrier
	v_readlane_b32 s40, v251, 28
	v_readlane_b32 s41, v251, 29
	v_and_b32_e32 v142, 0x3ff, v0
	v_lshrrev_b32_e32 v153, 4, v142
	v_and_b32_e32 v154, 15, v142
	v_lshlrev_b32_e32 v154, 4, v154
	v_lshlrev_b32_e32 v143, 16, v153
	v_add_u32_e32 v143, v143, v154
	v_mul_u32_u24_e32 v145, 0x104, v153
	v_add_u32_e32 v145, v145, v154
	v_add_u32_e32 v146, 0x2080, v145
	v_add_u32_e32 v147, 0x4100, v145
	v_add_u32_e32 v148, 0x6180, v145
	v_lshrrev_b32_e32 v153, 3, v142
	v_and_b32_e32 v154, 7, v142
	v_mul_u32_u24_e32 v149, 0x820, v154
	v_lshl_add_u32 v149, v153, 2, v149
	v_add_u32_e32 v150, 0x400, v149
	v_add_u32_e32 v151, 0x4100, v149
	v_add_u32_e32 v152, 0x4500, v149
	v_lshlrev_b32_e32 v144, 12, v153
	v_lshl_add_u32 v144, v154, 4, v144
	s_add_u32 s44, s64, 0x1c000000
	s_addc_u32 s45, s65, 0
	s_movk_i32 s54, 0x100
	s_add_i32 s46, s70, 0xffffff80
	s_waitcnt lgkmcnt(0)
	s_add_u32 s40, s40, 0xc000
	s_addc_u32 s41, s41, 0
	s_add_u32 s42, s40, 0x200000
	s_addc_u32 s43, s41, 0
	s_add_i32 s47, s46, 0x80
	s_cmpk_lt_i32 s47, 0x800
	s_cselect_b32 s47, s47, s46
	s_and_b32 s52, s46, 0x3f
	s_lshr_b32 s53, s46, 6
	s_lshl_b32 s52, s52, 8
	s_lshl_b32 s53, s53, 22
	s_add_i32 s48, s52, s53
	s_and_b32 s52, s47, 0x3f
	s_lshr_b32 s53, s47, 6
	s_lshl_b32 s52, s52, 8
	s_lshl_b32 s53, s53, 22
	s_add_i32 s49, s52, s53
	v_add_u32_e32 v153, s48, v143
	v_add_u32_e32 v172, s49, v143
	global_load_dwordx4 v[70:73], v153, s[40:41] nt
	global_load_dwordx4 v[74:77], v153, s[42:43] nt
	global_load_dwordx4 v[78:81], v172, s[40:41] nt
	global_load_dwordx4 v[82:85], v172, s[42:43] nt
	s_waitcnt vmcnt(0)
TCV5_body:
	ds_write2_b32 v145, v70, v71 offset1:1
	ds_write2_b32 v145, v72, v73 offset0:2 offset1:3
	ds_write2_b32 v146, v74, v75 offset1:1
	ds_write2_b32 v146, v76, v77 offset0:2 offset1:3
	ds_write2_b32 v147, v78, v79 offset1:1
	ds_write2_b32 v147, v80, v81 offset0:2 offset1:3
	ds_write2_b32 v148, v82, v83 offset1:1
	ds_write2_b32 v148, v84, v85 offset0:2 offset1:3
	s_and_b32 s52, s46, 0x3f
	s_lshr_b32 s53, s46, 6
	s_lshl_b32 s52, s52, 18
	s_lshl_b32 s53, s53, 7
	s_add_i32 s50, s52, s53
	s_and_b32 s52, s47, 0x3f
	s_lshr_b32 s53, s47, 6
	s_lshl_b32 s52, s52, 18
	s_lshl_b32 s53, s53, 7
	s_add_i32 s51, s52, s53
	s_waitcnt lgkmcnt(0)
	s_barrier
	s_add_i32 s46, s46, s54
	s_cmpk_lt_i32 s46, 0x800
	s_cbranch_scc0 TCV5_noload
	s_add_i32 s47, s46, 0x80
	s_cmpk_lt_i32 s47, 0x800
	s_cselect_b32 s47, s47, s46
	s_and_b32 s52, s46, 0x3f
	s_lshr_b32 s53, s46, 6
	s_lshl_b32 s52, s52, 8
	s_lshl_b32 s53, s53, 22
	s_add_i32 s48, s52, s53
	s_and_b32 s52, s47, 0x3f
	s_lshr_b32 s53, s47, 6
	s_lshl_b32 s52, s52, 8
	s_lshl_b32 s53, s53, 22
	s_add_i32 s49, s52, s53
	v_add_u32_e32 v153, s48, v143
	v_add_u32_e32 v172, s49, v143
	global_load_dwordx4 v[70:73], v153, s[40:41] nt
	global_load_dwordx4 v[74:77], v153, s[42:43] nt
	global_load_dwordx4 v[78:81], v172, s[40:41] nt
	global_load_dwordx4 v[82:85], v172, s[42:43] nt
TCV5_noload:
	ds_read2_b32 v[156:157], v149 offset1:65
	ds_read2_b32 v[158:159], v149 offset0:130 offset1:195
	ds_read2_b32 v[160:161], v150 offset0:4 offset1:69
	ds_read2_b32 v[162:163], v150 offset0:134 offset1:199
	ds_read2_b32 v[164:165], v151 offset1:65
	ds_read2_b32 v[166:167], v151 offset0:130 offset1:195
	ds_read2_b32 v[168:169], v152 offset0:4 offset1:69
	ds_read2_b32 v[170:171], v152 offset0:134 offset1:199
	v_add_u32_e32 v154, s50, v144
	v_add_u32_e32 v155, s51, v144
	s_waitcnt lgkmcnt(7)
	v_cvt_pk_bf16_f32 v156, v156, v157
	s_waitcnt lgkmcnt(6)
	v_cvt_pk_bf16_f32 v157, v158, v159
	s_waitcnt lgkmcnt(5)
	v_cvt_pk_bf16_f32 v158, v160, v161
	s_waitcnt lgkmcnt(4)
	v_cvt_pk_bf16_f32 v159, v162, v163
	global_store_dwordx4 v154, v[156:159], s[44:45]
	s_waitcnt lgkmcnt(3)
	v_cvt_pk_bf16_f32 v164, v164, v165
	s_waitcnt lgkmcnt(2)
	v_cvt_pk_bf16_f32 v165, v166, v167
	s_waitcnt lgkmcnt(1)
	v_cvt_pk_bf16_f32 v166, v168, v169
	s_waitcnt lgkmcnt(0)
	v_cvt_pk_bf16_f32 v167, v170, v171
	global_store_dwordx4 v155, v[164:167], s[44:45]
	s_barrier
	s_cmpk_lt_i32 s46, 0x800
	s_waitcnt vmcnt(2)
	s_cbranch_scc1 TCV5_body
	s_waitcnt vmcnt(0) lgkmcnt(0)
	s_barrier
	v_readlane_b32 s40, v250, 15
	v_readlane_b32 s41, v250, 16
	v_and_b32_e32 v142, 0x3ff, v0
	v_lshrrev_b32_e32 v153, 4, v142
	v_and_b32_e32 v154, 15, v142
	v_lshlrev_b32_e32 v154, 4, v154
	v_lshlrev_b32_e32 v143, 13, v153
	v_add_u32_e32 v143, v143, v154
	v_mul_u32_u24_e32 v145, 0x104, v153
	v_add_u32_e32 v145, v145, v154
	v_add_u32_e32 v146, 0x2080, v145
	v_add_u32_e32 v147, 0x4100, v145
	v_add_u32_e32 v148, 0x6180, v145
	v_lshrrev_b32_e32 v153, 3, v142
	v_and_b32_e32 v154, 7, v142
	v_mul_u32_u24_e32 v149, 0x820, v154
	v_lshl_add_u32 v149, v153, 2, v149
	v_add_u32_e32 v150, 0x400, v149
	v_add_u32_e32 v151, 0x4100, v149
	v_add_u32_e32 v152, 0x4500, v149
	v_lshlrev_b32_e32 v144, 13, v153
	v_lshl_add_u32 v144, v154, 4, v144
	s_add_u32 s44, s64, 0x1d000000
	s_addc_u32 s45, s65, 0
	s_movk_i32 s54, 0x100
	s_add_i32 s46, s70, 0xffffff80
	s_waitcnt lgkmcnt(0)
	s_add_u32 s42, s40, 0x40000
	s_addc_u32 s43, s41, 0
	s_add_i32 s47, s46, 0x80
	s_cmpk_lt_i32 s47, 0x800
	s_cselect_b32 s47, s47, s46
	s_and_b32 s52, s46, 0x1f
	s_lshr_b32 s53, s46, 5
	s_lshl_b32 s52, s52, 8
	s_lshl_b32 s53, s53, 19
	s_add_i32 s48, s52, s53
	s_and_b32 s52, s47, 0x1f
	s_lshr_b32 s53, s47, 5
	s_lshl_b32 s52, s52, 8
	s_lshl_b32 s53, s53, 19
	s_add_i32 s49, s52, s53
	v_add_u32_e32 v153, s48, v143
	v_add_u32_e32 v172, s49, v143
	global_load_dwordx4 v[70:73], v153, s[40:41] nt
	global_load_dwordx4 v[74:77], v153, s[42:43] nt
	global_load_dwordx4 v[78:81], v172, s[40:41] nt
	global_load_dwordx4 v[82:85], v172, s[42:43] nt
	s_waitcnt vmcnt(0)
; __device__ __forceinline__ u32x4 pack8(const float* f) { u32x4 w; w.x = pk2(f[0], f[1]); w.y = pk2(f[2], f[3]); w.z = pk2(f[4], f[5]); w.w = pk2(f[6], f[7]); return w; }
; #define SEAM(k) do { if (IN(k) && IN((k) + 1)) grid.sync(); if (PROBE_PH >= 0) { const unsigned long long tn_ = __builtin_amdgcn_s_memrealtime(); if ((PROBE_PH >> (k)) & 1) tp1 += tn_ - tp0; tp0 = tn_; } } while (0)
; __device__ void tconv(unsigned char* smem, const float* src, int ldsrc, int col0, int N, int K, u16* dst, int ldd) {
;     ...
;     for (; tile < ntile; tile += gridDim.x) {
;         const int tn = tile % tilesN, tk = tile / tilesN;
; #pragma unroll
;         for (int j = 0; j < 4; ++j) { T[lr * 65 + lc + j] = v0[j]; T[(lr + 32) * 65 + lc + j] = v1[j]; }
;         asm volatile("s_waitcnt lgkmcnt(0)" ::: "memory"); __builtin_amdgcn_s_barrier(); asm volatile("" ::: "memory");
;         const int nx = tile + gridDim.x;
;         if (nx < ntile) { const int tn2 = nx % tilesN, tk2 = nx / tilesN; const float* s = src + (size_t)(tk2 * 64 + lr) * ldsrc + col0 + tn2 * 64 + lc;
;             v0 = __builtin_nontemporal_load((const f32x4*)s); v1 = __builtin_nontemporal_load((const f32x4*)(s + (size_t)32 * ldsrc)); }
;         float f[8];
; #pragma unroll
;         for (int j = 0; j < 8; ++j) f[j] = T[(sk + j) * 65 + sn];
;         *(u32x4*)(dst + (size_t)(tn * 64 + sn) * ldd + tk * 64 + sk) = pack8(f);
;         asm volatile("s_waitcnt lgkmcnt(0)" ::: "memory"); __builtin_amdgcn_s_barrier(); asm volatile("" ::: "memory");
;     }
;     __syncthreads();
; __global__ void __launch_bounds__(512, 2) mega(Params p) {
;     ...
;     SEAM(8);
TCV6_body:
	ds_write2_b32 v145, v70, v71 offset1:1
	ds_write2_b32 v145, v72, v73 offset0:2 offset1:3
	ds_write2_b32 v146, v74, v75 offset1:1
	ds_write2_b32 v146, v76, v77 offset0:2 offset1:3
	ds_write2_b32 v147, v78, v79 offset1:1
	ds_write2_b32 v147, v80, v81 offset0:2 offset1:3
	ds_write2_b32 v148, v82, v83 offset1:1
	ds_write2_b32 v148, v84, v85 offset0:2 offset1:3
	s_and_b32 s52, s46, 0x1f
	s_lshr_b32 s53, s46, 5
	s_lshl_b32 s52, s52, 19
	s_lshl_b32 s53, s53, 7
	s_add_i32 s50, s52, s53
	s_and_b32 s52, s47, 0x1f
	s_lshr_b32 s53, s47, 5
	s_lshl_b32 s52, s52, 19
	s_lshl_b32 s53, s53, 7
	s_add_i32 s51, s52, s53
	s_waitcnt lgkmcnt(0)
	s_barrier
	s_add_i32 s46, s46, s54
	s_cmpk_lt_i32 s46, 0x800
	s_cbranch_scc0 TCV6_noload
	s_add_i32 s47, s46, 0x80
	s_cmpk_lt_i32 s47, 0x800
	s_cselect_b32 s47, s47, s46
	s_and_b32 s52, s46, 0x1f
	s_lshr_b32 s53, s46, 5
	s_lshl_b32 s52, s52, 8
	s_lshl_b32 s53, s53, 19
	s_add_i32 s48, s52, s53
	s_and_b32 s52, s47, 0x1f
	s_lshr_b32 s53, s47, 5
	s_lshl_b32 s52, s52, 8
	s_lshl_b32 s53, s53, 19
	s_add_i32 s49, s52, s53
	v_add_u32_e32 v153, s48, v143
	v_add_u32_e32 v172, s49, v143
	global_load_dwordx4 v[70:73], v153, s[40:41] nt
	global_load_dwordx4 v[74:77], v153, s[42:43] nt
	global_load_dwordx4 v[78:81], v172, s[40:41] nt
	global_load_dwordx4 v[82:85], v172, s[42:43] nt
TCV6_noload:
	ds_read2_b32 v[156:157], v149 offset1:65
	ds_read2_b32 v[158:159], v149 offset0:130 offset1:195
	ds_read2_b32 v[160:161], v150 offset0:4 offset1:69
	ds_read2_b32 v[162:163], v150 offset0:134 offset1:199
	ds_read2_b32 v[164:165], v151 offset1:65
	ds_read2_b32 v[166:167], v151 offset0:130 offset1:195
	ds_read2_b32 v[168:169], v152 offset0:4 offset1:69
	ds_read2_b32 v[170:171], v152 offset0:134 offset1:199
	v_add_u32_e32 v154, s50, v144
	v_add_u32_e32 v155, s51, v144
	s_waitcnt lgkmcnt(7)
	v_cvt_pk_bf16_f32 v156, v156, v157
	s_waitcnt lgkmcnt(6)
	v_cvt_pk_bf16_f32 v157, v158, v159
	s_waitcnt lgkmcnt(5)
	v_cvt_pk_bf16_f32 v158, v160, v161
	s_waitcnt lgkmcnt(4)
	v_cvt_pk_bf16_f32 v159, v162, v163
	global_store_dwordx4 v154, v[156:159], s[44:45]
	s_waitcnt lgkmcnt(3)
	v_cvt_pk_bf16_f32 v164, v164, v165
	s_waitcnt lgkmcnt(2)
	v_cvt_pk_bf16_f32 v165, v166, v167
	s_waitcnt lgkmcnt(1)
	v_cvt_pk_bf16_f32 v166, v168, v169
	s_waitcnt lgkmcnt(0)
	v_cvt_pk_bf16_f32 v167, v170, v171
	global_store_dwordx4 v155, v[164:167], s[44:45]
	s_barrier
	s_cmpk_lt_i32 s46, 0x800
	s_waitcnt vmcnt(2)
	s_cbranch_scc1 TCV6_body
	s_waitcnt lgkmcnt(0)
	s_barrier
P8IDLE_skip:
.LBB0_814:
	s_cmp_gt_i32 s67, 9
	s_cselect_b64 s[0:1], -1, 0
	s_and_b64 s[2:3], s[6:7], s[0:1]
	s_andn2_b64 vcc, exec, s[2:3]
	s_cbranch_vccnz .LBB0_826
	v_and_b32_e32 v1, 0x3fffffff, v0
	v_cmp_eq_u32_e32 vcc, 0, v1
	s_waitcnt vmcnt(0) lgkmcnt(0)
	s_barrier
	s_and_saveexec_b64 s[2:3], vcc
	s_cbranch_execz .LBB0_825
	s_load_dwordx2 s[4:5], s[68:69], 0x58
	s_getreg_b32 s101, hwreg(HW_REG_XCC_ID)
	s_and_b32 s101, s101, 7
	s_lshr_b32 s98, s101, 1
	s_lshl_b32 s98, s98, 2
	s_and_b32 s99, s101, 1
	s_lshl_b32 s99, s99, 4
	v_mov_b32_e32 v3, s98
	v_mov_b32_e32 v1, 1
	v_lshlrev_b32_e32 v1, s99, v1
	s_waitcnt vmcnt(0) lgkmcnt(0)
	global_atomic_add v2, v3, v1, s[4:5] offset:16 sc0
	s_load_dword s101, s[4:5], 0x28
	s_waitcnt vmcnt(0)
	v_lshrrev_b32_e32 v2, s99, v2
	v_and_b32_e32 v2, 0xffff, v2
	v_add_u32_e32 v2, 1, v2
	s_and_b32 s98, s100, 0xff
	s_add_u32 s98, s98, 2
	s_bfe_u32 s99, s100, 0x80008
	s_mul_i32 s98, s98, s99
	v_mov_b32_e32 v4, 0
	v_mov_b32_e32 v1, 1
	v_cmp_eq_u32_e32 vcc, s98, v2
	s_waitcnt lgkmcnt(0)
	s_and_b32 s98, s100, 0xff
	s_add_u32 s98, s98, 1
	s_bfe_u32 s99, s100, 0x80010
	s_mul_i32 s99, s99, s98
	s_add_u32 s99, s99, s101
	s_add_u32 s100, s100, 1
	s_and_saveexec_b64 s[6:7], vcc
	s_cbranch_execz .Lhs_nl_8
	buffer_wbl2 sc1
	s_waitcnt vmcnt(0)
	global_atomic_add v4, v1, s[4:5] offset:36
